# v059 + dead ai=1 A-fragment LDS reads removed from the half-M main-loop copy
# speedup vs baseline: 1.0071x; 1.0030x over previous
; #define WAIT_V(n) asm volatile("s_waitcnt vmcnt(" #n ")" ::: "memory")
; #define WAIT_L(n) asm volatile("s_waitcnt lgkmcnt(" #n ")" ::: "memory")
; #define BAR __builtin_amdgcn_s_barrier()
; #define SCHED __builtin_amdgcn_sched_barrier(0)
; DEVI void gemm256(const P& p, const u16* A, int lda, const u16* Bt, int ldb, int K, int brow, int bcol, int mode,
;                         int aux, int layer, int bmode) {
;     ...
;   for (int t = 0; t < nt - 2; t += 2) {
;     LDB(B0, 0, 0); SCHED; LDA(At, 0, 0); STAGEA(SA(1, 1), brow + HALF, t + 1);
;     WAIT_L(8); BAR; WAIT_L(0); MMA(0, 0, At, B0); BAR; SCHED;
;     LDB(B1, 0, 1); STAGEB(SB(0, 0), bcol, t + 2);
;     BAR; WAIT_L(0); MMA(0, 1, At, B1); BAR;
;     LDA(At, 0, 1); STAGEA(SA(0, 0), brow, t + 2);
;     BAR; WAIT_L(0); MMA(1, 0, At, B0); BAR; SCHED;
;     STAGEB(SB(0, 1), bcol + bhalf, t + 2);
;     WAIT_V(6); BAR; MMA(1, 1, At, B1); BAR;
;     LDB(B0, 1, 0); SCHED; LDA(At, 1, 0); STAGEA(SA(0, 1), brow + HALF, t + 2);
;     WAIT_L(8); BAR; WAIT_L(0); MMA(0, 0, At, B0); BAR; SCHED;
;     LDB(B1, 1, 1); STAGEB(SB(1, 0), bcol, t + 3);
;     BAR; WAIT_L(0); MMA(0, 1, At, B1); BAR;
;     LDA(At, 1, 1); STAGEA(SA(1, 0), brow, t + 3);
;     BAR; WAIT_L(0); MMA(1, 0, At, B0); BAR; SCHED;
;     STAGEB(SB(1, 1), bcol + bhalf, t + 3);
;     WAIT_V(6); BAR; MMA(1, 1, At, B1); BAR;
.Lhm_192:
	ds_read_b128 v[164:167], v163
	ds_read_b128 v[172:175], v163 offset:1024
	ds_read_b128 v[176:179], v163 offset:2048
	ds_read_b128 v[180:183], v163 offset:3072
	s_add_i32 s12, s3, s10
	v_readfirstlane_b32 s14, v159
	s_add_i32 s13, s12, 0x80
	s_mov_b32 m0, s14
	v_readfirstlane_b32 s14, v158
	ds_read_b128 v[184:187], v141
	ds_read_b128 v[188:191], v141 offset:1024
	ds_read_b128 v[204:207], v140
	ds_read_b128 v[208:211], v140 offset:1024
	ds_read_b128 v[212:215], v139
	ds_read_b128 v[216:219], v139 offset:1024
	ds_read_b128 v[220:223], v138
	ds_read_b128 v[224:227], v138 offset:1024
	buffer_load_dwordx4 v143, s[44:47], s13 offen lds
	s_mov_b32 m0, s14
	s_nop 0
	buffer_load_dwordx4 v142, s[44:47], s13 offen lds
	s_waitcnt lgkmcnt(8)
	s_barrier
	s_waitcnt lgkmcnt(0)
	s_setprio 1
	s_waitcnt lgkmcnt(7)
	v_mfma_f32_16x16x32_bf16 v[126:129], v[164:167], v[184:187], v[126:129]
	v_mfma_f32_16x16x32_bf16 v[122:125], v[176:179], v[184:187], v[122:125]
	s_waitcnt lgkmcnt(5)
	v_mfma_f32_16x16x32_bf16 v[118:121], v[164:167], v[204:207], v[118:121]
	v_mfma_f32_16x16x32_bf16 v[114:117], v[176:179], v[204:207], v[114:117]
	s_waitcnt lgkmcnt(3)
	v_mfma_f32_16x16x32_bf16 v[110:113], v[164:167], v[212:215], v[110:113]
	v_mfma_f32_16x16x32_bf16 v[98:101], v[176:179], v[212:215], v[98:101]
	s_waitcnt lgkmcnt(1)
	v_mfma_f32_16x16x32_bf16 v[82:85], v[164:167], v[220:223], v[82:85]
	v_mfma_f32_16x16x32_bf16 v[62:65], v[176:179], v[220:223], v[62:65]
	v_mfma_f32_16x16x32_bf16 v[126:129], v[172:175], v[188:191], v[126:129]
	v_mfma_f32_16x16x32_bf16 v[122:125], v[180:183], v[188:191], v[122:125]
	v_mfma_f32_16x16x32_bf16 v[118:121], v[172:175], v[208:211], v[118:121]
	v_mfma_f32_16x16x32_bf16 v[114:117], v[180:183], v[208:211], v[114:117]
	v_mfma_f32_16x16x32_bf16 v[110:113], v[172:175], v[216:219], v[110:113]
	v_mfma_f32_16x16x32_bf16 v[98:101], v[180:183], v[216:219], v[98:101]
	s_waitcnt lgkmcnt(0)
	v_mfma_f32_16x16x32_bf16 v[82:85], v[172:175], v[224:227], v[82:85]
	v_mfma_f32_16x16x32_bf16 v[62:65], v[180:183], v[224:227], v[62:65]
	s_setprio 0
	s_barrier
	s_add_i32 s13, s6, s10
	v_readfirstlane_b32 s15, v145
	s_add_i32 s14, s13, 0x100
	s_mov_b32 m0, s15
	v_readfirstlane_b32 s15, v146
	ds_read_b128 v[228:231], v160
	ds_read_b128 v[232:235], v160 offset:1024
	ds_read_b128 v[236:239], v160 offset:2048
	ds_read_b128 v[240:243], v160 offset:3072
	buffer_load_dwordx4 v136, s[28:31], s14 offen lds
	s_mov_b32 m0, s15
	s_add_i32 s11, s11, 2
	buffer_load_dwordx4 v137, s[28:31], s14 offen lds
	s_barrier
	s_waitcnt lgkmcnt(0)
	s_setprio 1
	s_waitcnt lgkmcnt(3)
	v_mfma_f32_16x16x32_bf16 v[30:33], v[228:231], v[184:187], v[30:33]
	s_waitcnt lgkmcnt(1)
	v_mfma_f32_16x16x32_bf16 v[26:29], v[236:239], v[184:187], v[26:29]
	v_mfma_f32_16x16x32_bf16 v[22:25], v[228:231], v[204:207], v[22:25]
	v_mfma_f32_16x16x32_bf16 v[18:21], v[236:239], v[204:207], v[18:21]
	v_mfma_f32_16x16x32_bf16 v[14:17], v[228:231], v[212:215], v[14:17]
	v_mfma_f32_16x16x32_bf16 v[10:13], v[236:239], v[212:215], v[10:13]
	v_mfma_f32_16x16x32_bf16 v[6:9], v[228:231], v[220:223], v[6:9]
	v_mfma_f32_16x16x32_bf16 v[2:5], v[236:239], v[220:223], v[2:5]
	v_mfma_f32_16x16x32_bf16 v[30:33], v[232:235], v[188:191], v[30:33]
	s_waitcnt lgkmcnt(0)
	v_mfma_f32_16x16x32_bf16 v[26:29], v[240:243], v[188:191], v[26:29]
	v_mfma_f32_16x16x32_bf16 v[22:25], v[232:235], v[208:211], v[22:25]
	v_mfma_f32_16x16x32_bf16 v[18:21], v[240:243], v[208:211], v[18:21]
	v_mfma_f32_16x16x32_bf16 v[14:17], v[232:235], v[216:219], v[14:17]
	v_mfma_f32_16x16x32_bf16 v[10:13], v[240:243], v[216:219], v[10:13]
	v_mfma_f32_16x16x32_bf16 v[6:9], v[232:235], v[224:227], v[6:9]
	v_mfma_f32_16x16x32_bf16 v[2:5], v[240:243], v[224:227], v[2:5]
	s_setprio 0
	s_add_i32 s14, s9, s10
	v_readfirstlane_b32 s16, v147
	s_add_i32 s15, s14, 0x100
	s_mov_b32 m0, s16
	v_readfirstlane_b32 s16, v148
	s_barrier
	buffer_load_dwordx4 v143, s[44:47], s15 offen lds
	s_mov_b32 m0, s16
	s_nop 0
	buffer_load_dwordx4 v142, s[44:47], s15 offen lds
	s_barrier
	s_waitcnt lgkmcnt(0)
	s_barrier
	s_add_i32 s15, s8, s10
	v_readfirstlane_b32 s17, v150
	s_add_i32 s16, s15, 0x100
	s_mov_b32 m0, s17
	v_readfirstlane_b32 s17, v151
	buffer_load_dwordx4 v136, s[28:31], s16 offen lds
	s_mov_b32 m0, s17
	s_nop 0
	buffer_load_dwordx4 v137, s[28:31], s16 offen lds
	s_waitcnt vmcnt(6)
	s_barrier
	s_barrier
	ds_read_b128 v[164:167], v149
	ds_read_b128 v[172:175], v149 offset:1024
	ds_read_b128 v[176:179], v149 offset:2048
	ds_read_b128 v[180:183], v149 offset:3072
	v_readfirstlane_b32 s16, v152
	s_addk_i32 s12, 0x100
	s_mov_b32 m0, s16
	v_readfirstlane_b32 s16, v153
	ds_read_b128 v[184:187], v141 offset:32768
	ds_read_b128 v[188:191], v141 offset:33792
	ds_read_b128 v[204:207], v140 offset:32768
	ds_read_b128 v[208:211], v140 offset:33792
	ds_read_b128 v[212:215], v139 offset:32768
	ds_read_b128 v[216:219], v139 offset:33792
	ds_read_b128 v[220:223], v138 offset:32768
	ds_read_b128 v[224:227], v138 offset:33792
	buffer_load_dwordx4 v143, s[44:47], s12 offen lds
	s_mov_b32 m0, s16
	s_nop 0
	buffer_load_dwordx4 v142, s[44:47], s12 offen lds
	s_waitcnt lgkmcnt(8)
	s_barrier
; #define WAIT_V(n) asm volatile("s_waitcnt vmcnt(" #n ")" ::: "memory")
; #define WAIT_L(n) asm volatile("s_waitcnt lgkmcnt(" #n ")" ::: "memory")
; #define BAR __builtin_amdgcn_s_barrier()
; #define SCHED __builtin_amdgcn_sched_barrier(0)
; DEVI void gemm256(const P& p, const u16* A, int lda, const u16* Bt, int ldb, int K, int brow, int bcol, int mode,
;                         int aux, int layer, int bmode) {
;     ...
;     LDB(B0, 1, 0); SCHED; LDA(At, 1, 0); STAGEA(SA(0, 1), brow + HALF, t + 2);
;     WAIT_L(8); BAR; WAIT_L(0); MMA(0, 0, At, B0); BAR; SCHED;
;     LDB(B1, 1, 1); STAGEB(SB(1, 0), bcol, t + 3);
;     BAR; WAIT_L(0); MMA(0, 1, At, B1); BAR;
;     LDA(At, 1, 1); STAGEA(SA(1, 0), brow, t + 3);
;     BAR; WAIT_L(0); MMA(1, 0, At, B0); BAR; SCHED;
;     STAGEB(SB(1, 1), bcol + bhalf, t + 3);
;     WAIT_V(6); BAR; MMA(1, 1, At, B1); BAR;
;   }
;   {
;     LDB(B0, 0, 0); LDA(At, 0, 0); STAGEA(SA(1, 1), brow + HALF, nt - 1);
;     BAR; WAIT_L(0); MMA(0, 0, At, B0); BAR;
	s_waitcnt lgkmcnt(0)
	s_setprio 1
	s_waitcnt lgkmcnt(7)
	v_mfma_f32_16x16x32_bf16 v[126:129], v[164:167], v[184:187], v[126:129]
	v_mfma_f32_16x16x32_bf16 v[122:125], v[176:179], v[184:187], v[122:125]
	s_waitcnt lgkmcnt(5)
	v_mfma_f32_16x16x32_bf16 v[118:121], v[164:167], v[204:207], v[118:121]
	v_mfma_f32_16x16x32_bf16 v[114:117], v[176:179], v[204:207], v[114:117]
	s_waitcnt lgkmcnt(3)
	v_mfma_f32_16x16x32_bf16 v[110:113], v[164:167], v[212:215], v[110:113]
	v_mfma_f32_16x16x32_bf16 v[98:101], v[176:179], v[212:215], v[98:101]
	s_waitcnt lgkmcnt(1)
	v_mfma_f32_16x16x32_bf16 v[82:85], v[164:167], v[220:223], v[82:85]
	v_mfma_f32_16x16x32_bf16 v[62:65], v[176:179], v[220:223], v[62:65]
	v_mfma_f32_16x16x32_bf16 v[126:129], v[172:175], v[188:191], v[126:129]
	v_mfma_f32_16x16x32_bf16 v[122:125], v[180:183], v[188:191], v[122:125]
	v_mfma_f32_16x16x32_bf16 v[118:121], v[172:175], v[208:211], v[118:121]
	v_mfma_f32_16x16x32_bf16 v[114:117], v[180:183], v[208:211], v[114:117]
	v_mfma_f32_16x16x32_bf16 v[110:113], v[172:175], v[216:219], v[110:113]
	v_mfma_f32_16x16x32_bf16 v[98:101], v[180:183], v[216:219], v[98:101]
	s_waitcnt lgkmcnt(0)
	v_mfma_f32_16x16x32_bf16 v[82:85], v[172:175], v[224:227], v[82:85]
	v_mfma_f32_16x16x32_bf16 v[62:65], v[180:183], v[224:227], v[62:65]
	s_setprio 0
	s_barrier
	v_readfirstlane_b32 s12, v154
	s_addk_i32 s13, 0x180
	s_mov_b32 m0, s12
	v_readfirstlane_b32 s12, v155
	ds_read_b128 v[228:231], v144
	ds_read_b128 v[232:235], v144 offset:1024
	ds_read_b128 v[236:239], v144 offset:2048
	ds_read_b128 v[240:243], v144 offset:3072
	buffer_load_dwordx4 v136, s[28:31], s13 offen lds
	s_mov_b32 m0, s12
	s_nop 0
	buffer_load_dwordx4 v137, s[28:31], s13 offen lds
	s_barrier
	s_waitcnt lgkmcnt(0)
	s_setprio 1
	s_waitcnt lgkmcnt(3)
	v_mfma_f32_16x16x32_bf16 v[30:33], v[228:231], v[184:187], v[30:33]
	s_waitcnt lgkmcnt(1)
	v_mfma_f32_16x16x32_bf16 v[26:29], v[236:239], v[184:187], v[26:29]
	v_mfma_f32_16x16x32_bf16 v[22:25], v[228:231], v[204:207], v[22:25]
	v_mfma_f32_16x16x32_bf16 v[18:21], v[236:239], v[204:207], v[18:21]
	v_mfma_f32_16x16x32_bf16 v[14:17], v[228:231], v[212:215], v[14:17]
	v_mfma_f32_16x16x32_bf16 v[10:13], v[236:239], v[212:215], v[10:13]
	v_mfma_f32_16x16x32_bf16 v[6:9], v[228:231], v[220:223], v[6:9]
	v_mfma_f32_16x16x32_bf16 v[2:5], v[236:239], v[220:223], v[2:5]
	v_mfma_f32_16x16x32_bf16 v[30:33], v[232:235], v[188:191], v[30:33]
	s_waitcnt lgkmcnt(0)
	v_mfma_f32_16x16x32_bf16 v[26:29], v[240:243], v[188:191], v[26:29]
	v_mfma_f32_16x16x32_bf16 v[22:25], v[232:235], v[208:211], v[22:25]
	v_mfma_f32_16x16x32_bf16 v[18:21], v[240:243], v[208:211], v[18:21]
	v_mfma_f32_16x16x32_bf16 v[14:17], v[232:235], v[216:219], v[14:17]
	v_mfma_f32_16x16x32_bf16 v[10:13], v[240:243], v[216:219], v[10:13]
	v_mfma_f32_16x16x32_bf16 v[6:9], v[232:235], v[224:227], v[6:9]
	v_mfma_f32_16x16x32_bf16 v[2:5], v[240:243], v[224:227], v[2:5]
	s_setprio 0
	v_readfirstlane_b32 s12, v156
	s_addk_i32 s14, 0x180
	s_mov_b32 m0, s12
	v_readfirstlane_b32 s12, v157
	s_barrier
	buffer_load_dwordx4 v143, s[44:47], s14 offen lds
	s_mov_b32 m0, s12
	s_nop 0
	buffer_load_dwordx4 v142, s[44:47], s14 offen lds
	s_barrier
	s_waitcnt lgkmcnt(0)
	s_barrier
	v_readfirstlane_b32 s12, v161
	s_addk_i32 s15, 0x180
	s_mov_b32 m0, s12
	v_readfirstlane_b32 s12, v162
	buffer_load_dwordx4 v136, s[28:31], s15 offen lds
	s_mov_b32 m0, s12
	s_nop 0
	buffer_load_dwordx4 v137, s[28:31], s15 offen lds
	s_waitcnt vmcnt(6)
	s_barrier
	s_addk_i32 s10, 0x100
	s_cmp_lt_u32 s11, s2
	s_barrier
	s_cbranch_scc1 .Lhm_192
	s_add_i32 s2, s5, s7
	s_lshl_b32 s2, s2, 1
	v_readfirstlane_b32 s3, v159
	s_addk_i32 s2, 0xff80
	s_mov_b32 s46, s30
	s_mov_b32 s47, s31
	s_mov_b32 m0, s3
	v_readfirstlane_b32 s3, v158
	ds_read_b128 v[150:153], v163
	ds_read_b128 v[154:157], v163 offset:1024
	ds_read_b128 v[164:167], v163 offset:2048
	ds_read_b128 v[172:175], v163 offset:3072
	ds_read_b128 v[176:179], v141
	ds_read_b128 v[180:183], v141 offset:1024
	ds_read_b128 v[184:187], v140
	ds_read_b128 v[188:191], v140 offset:1024
	ds_read_b128 v[204:207], v139
	ds_read_b128 v[208:211], v139 offset:1024
	ds_read_b128 v[212:215], v138
	ds_read_b128 v[216:219], v138 offset:1024
	buffer_load_dwordx4 v143, s[44:47], s2 offen lds
	s_mov_b32 m0, s3
	s_nop 0
	buffer_load_dwordx4 v142, s[44:47], s2 offen lds
	s_barrier
	s_waitcnt lgkmcnt(0)
	s_setprio 1
	s_waitcnt lgkmcnt(7)
	v_mfma_f32_16x16x32_bf16 v[126:129], v[150:153], v[176:179], v[126:129]
	v_mfma_f32_16x16x32_bf16 v[122:125], v[164:167], v[176:179], v[122:125]
	s_waitcnt lgkmcnt(5)
	v_mfma_f32_16x16x32_bf16 v[118:121], v[150:153], v[184:187], v[118:121]
	v_mfma_f32_16x16x32_bf16 v[114:117], v[164:167], v[184:187], v[114:117]
	s_waitcnt lgkmcnt(3)
	v_mfma_f32_16x16x32_bf16 v[110:113], v[150:153], v[204:207], v[110:113]
	v_mfma_f32_16x16x32_bf16 v[98:101], v[164:167], v[204:207], v[98:101]
	s_waitcnt lgkmcnt(1)
	v_mfma_f32_16x16x32_bf16 v[82:85], v[150:153], v[212:215], v[82:85]
	v_mfma_f32_16x16x32_bf16 v[62:65], v[164:167], v[212:215], v[62:65]
	v_mfma_f32_16x16x32_bf16 v[126:129], v[154:157], v[180:183], v[126:129]
	v_mfma_f32_16x16x32_bf16 v[122:125], v[172:175], v[180:183], v[122:125]
	v_mfma_f32_16x16x32_bf16 v[118:121], v[154:157], v[188:191], v[118:121]
	v_mfma_f32_16x16x32_bf16 v[114:117], v[172:175], v[188:191], v[114:117]
	v_mfma_f32_16x16x32_bf16 v[110:113], v[154:157], v[208:211], v[110:113]
	v_mfma_f32_16x16x32_bf16 v[98:101], v[172:175], v[208:211], v[98:101]
	s_waitcnt lgkmcnt(0)
	v_mfma_f32_16x16x32_bf16 v[82:85], v[154:157], v[216:219], v[82:85]
	v_mfma_f32_16x16x32_bf16 v[62:65], v[172:175], v[216:219], v[62:65]
	s_setprio 0
	s_barrier
; #define WAIT_V(n) asm volatile("s_waitcnt vmcnt(" #n ")" ::: "memory")
; #define WAIT_L(n) asm volatile("s_waitcnt lgkmcnt(" #n ")" ::: "memory")
; #define BAR __builtin_amdgcn_s_barrier()
; DEVI void gemm256(const P& p, const u16* A, int lda, const u16* Bt, int ldb, int K, int brow, int bcol, int mode,
;                         int aux, int layer, int bmode) {
;     ...
;     LDB(B1, 0, 1); BAR; WAIT_L(0); MMA(0, 1, At, B1); BAR;
;     LDA(At, 0, 1); WAIT_V(4); BAR; WAIT_L(0); MMA(1, 0, At, B0); MMA(1, 1, At, B1); BAR;
;   }
;   {
;     LDB(B0, 1, 0); LDA(At, 1, 0); WAIT_V(2); BAR; WAIT_L(0); MMA(0, 0, At, B0); BAR;
;     LDB(B1, 1, 1); WAIT_V(0); BAR; WAIT_L(0); MMA(0, 1, At, B1); BAR;
;     LDA(At, 1, 1); BAR; WAIT_L(0); MMA(1, 0, At, B0); MMA(1, 1, At, B1); BAR;
	ds_read_b128 v[220:223], v160
	ds_read_b128 v[224:227], v160 offset:1024
	ds_read_b128 v[228:231], v160 offset:2048
	ds_read_b128 v[158:161], v160 offset:3072
	s_barrier
	s_waitcnt lgkmcnt(0)
	s_setprio 1
	s_waitcnt lgkmcnt(3)
	v_mfma_f32_16x16x32_bf16 v[30:33], v[220:223], v[176:179], v[30:33]
	s_waitcnt lgkmcnt(1)
	v_mfma_f32_16x16x32_bf16 v[26:29], v[228:231], v[176:179], v[26:29]
	v_mfma_f32_16x16x32_bf16 v[22:25], v[220:223], v[184:187], v[22:25]
	v_mfma_f32_16x16x32_bf16 v[18:21], v[228:231], v[184:187], v[18:21]
	v_mfma_f32_16x16x32_bf16 v[14:17], v[220:223], v[204:207], v[14:17]
	v_mfma_f32_16x16x32_bf16 v[10:13], v[228:231], v[204:207], v[10:13]
	v_mfma_f32_16x16x32_bf16 v[6:9], v[220:223], v[212:215], v[6:9]
	v_mfma_f32_16x16x32_bf16 v[2:5], v[228:231], v[212:215], v[2:5]
	v_mfma_f32_16x16x32_bf16 v[30:33], v[224:227], v[180:183], v[30:33]
	s_waitcnt lgkmcnt(0)
	v_mfma_f32_16x16x32_bf16 v[26:29], v[158:161], v[180:183], v[26:29]
	v_mfma_f32_16x16x32_bf16 v[22:25], v[224:227], v[188:191], v[22:25]
	v_mfma_f32_16x16x32_bf16 v[18:21], v[158:161], v[188:191], v[18:21]
	v_mfma_f32_16x16x32_bf16 v[14:17], v[224:227], v[208:211], v[14:17]
	v_mfma_f32_16x16x32_bf16 v[10:13], v[158:161], v[208:211], v[10:13]
	v_mfma_f32_16x16x32_bf16 v[6:9], v[224:227], v[216:219], v[6:9]
	v_mfma_f32_16x16x32_bf16 v[2:5], v[158:161], v[216:219], v[2:5]
	s_setprio 0
	s_barrier
	s_waitcnt vmcnt(4)
	s_barrier
	s_waitcnt lgkmcnt(0)
	s_barrier
	ds_read_b128 v[204:207], v149
	ds_read_b128 v[208:211], v149 offset:1024
	ds_read_b128 v[212:215], v149 offset:2048
	ds_read_b128 v[146:149], v149 offset:3072
	s_nop 0
	ds_read_b128 v[50:53], v141 offset:32768
	ds_read_b128 v[54:57], v141 offset:33792
	ds_read_b128 v[58:61], v140 offset:32768
	ds_read_b128 v[66:69], v140 offset:33792
	ds_read_b128 v[70:73], v139 offset:32768
	ds_read_b128 v[78:81], v139 offset:33792
	ds_read_b128 v[216:219], v138 offset:32768
	ds_read_b128 v[220:223], v138 offset:33792
	s_waitcnt vmcnt(2)
	s_barrier
	s_waitcnt lgkmcnt(0)
	s_setprio 1
	s_waitcnt lgkmcnt(7)
	v_mfma_f32_16x16x32_bf16 v[74:77], v[204:207], v[50:53], v[126:129]
	s_waitcnt lgkmcnt(6)
	v_mfma_f32_16x16x32_bf16 v[126:129], v[208:211], v[54:57], v[74:77]
	v_mfma_f32_16x16x32_bf16 v[74:77], v[212:215], v[50:53], v[122:125]
	v_mfma_f32_16x16x32_bf16 v[122:125], v[146:149], v[54:57], v[74:77]
	s_waitcnt lgkmcnt(5)
	v_mfma_f32_16x16x32_bf16 v[74:77], v[204:207], v[58:61], v[118:121]
	s_waitcnt lgkmcnt(4)
	v_mfma_f32_16x16x32_bf16 v[118:121], v[208:211], v[66:69], v[74:77]
	v_mfma_f32_16x16x32_bf16 v[74:77], v[212:215], v[58:61], v[114:117]
	v_mfma_f32_16x16x32_bf16 v[114:117], v[146:149], v[66:69], v[74:77]
	s_waitcnt lgkmcnt(3)
	v_mfma_f32_16x16x32_bf16 v[74:77], v[204:207], v[70:73], v[110:113]
	s_waitcnt lgkmcnt(2)
	v_mfma_f32_16x16x32_bf16 v[110:113], v[208:211], v[78:81], v[74:77]
	v_mfma_f32_16x16x32_bf16 v[74:77], v[212:215], v[70:73], v[98:101]
	v_mfma_f32_16x16x32_bf16 v[102:105], v[146:149], v[78:81], v[74:77]
	s_waitcnt lgkmcnt(1)
	v_mfma_f32_16x16x32_bf16 v[74:77], v[204:207], v[216:219], v[82:85]
	v_mfma_f32_16x16x32_bf16 v[62:65], v[212:215], v[216:219], v[62:65]
	s_waitcnt lgkmcnt(0)
	v_mfma_f32_16x16x32_bf16 v[98:101], v[208:211], v[220:223], v[74:77]
	v_mfma_f32_16x16x32_bf16 v[90:93], v[146:149], v[220:223], v[62:65]
	s_setprio 0
	s_barrier
	ds_read_b128 v[224:227], v144
	ds_read_b128 v[228:231], v144 offset:1024
	ds_read_b128 v[240:243], v144 offset:2048
	ds_read_b128 v[142:145], v144 offset:3072
	s_waitcnt vmcnt(0)
	s_barrier
	s_waitcnt lgkmcnt(0)
	s_setprio 1
	s_waitcnt lgkmcnt(3)
	v_mfma_f32_16x16x32_bf16 v[30:33], v[224:227], v[50:53], v[30:33]
	s_waitcnt lgkmcnt(1)
	v_mfma_f32_16x16x32_bf16 v[26:29], v[240:243], v[50:53], v[26:29]
	v_mfma_f32_16x16x32_bf16 v[22:25], v[224:227], v[58:61], v[22:25]
	v_mfma_f32_16x16x32_bf16 v[18:21], v[240:243], v[58:61], v[18:21]
	v_mfma_f32_16x16x32_bf16 v[14:17], v[224:227], v[70:73], v[14:17]
	v_mfma_f32_16x16x32_bf16 v[10:13], v[240:243], v[70:73], v[10:13]
	v_mfma_f32_16x16x32_bf16 v[6:9], v[224:227], v[216:219], v[6:9]
	v_mfma_f32_16x16x32_bf16 v[2:5], v[240:243], v[216:219], v[2:5]
	v_mfma_f32_16x16x32_bf16 v[106:109], v[228:231], v[54:57], v[30:33]
	s_waitcnt lgkmcnt(0)
	v_mfma_f32_16x16x32_bf16 v[94:97], v[142:145], v[54:57], v[26:29]
	v_mfma_f32_16x16x32_bf16 v[86:89], v[228:231], v[66:69], v[22:25]
	v_mfma_f32_16x16x32_bf16 v[82:85], v[142:145], v[66:69], v[18:21]
	v_mfma_f32_16x16x32_bf16 v[74:77], v[228:231], v[78:81], v[14:17]
	v_mfma_f32_16x16x32_bf16 v[66:69], v[142:145], v[78:81], v[10:13]
	v_mfma_f32_16x16x32_bf16 v[62:65], v[228:231], v[220:223], v[6:9]
	v_mfma_f32_16x16x32_bf16 v[54:57], v[142:145], v[220:223], v[2:5]
	s_setprio 0
	s_barrier
	s_nop 0
	s_barrier
	s_waitcnt lgkmcnt(0)
